# v20: v4 plus non-temporal hint on the write-only f32 K/V output stores of the QKV projection epilogue (precision unchanged)
# speedup vs baseline: 1.0028x; 1.0028x over previous
.LBB0_1097:
	v_lshl_add_u32 v144, s8, 8, v152
	s_lshl_b32 s8, s9, 8
	s_lshl_b32 s9, s35, 10
	s_sub_i32 s8, s8, s9
	v_or_b32_e32 v146, s8, v154
	v_ashrrev_i32_e32 v145, 31, v144
	v_ashrrev_i32_e32 v147, 31, v146
	v_lshlrev_b64 v[148:149], 10, v[144:145]
	v_lshl_add_u64 v[150:151], v[148:149], 0, v[146:147]
	v_lshl_add_u64 v[148:149], v[150:151], 2, s[36:37]
	s_mov_b64 s[8:9], -1
	s_and_b64 vcc, exec, s[30:31]
	s_cbranch_vccz .LBB0_1099
	global_store_dwordx4 v[148:149], v[124:127], off nt
	global_store_dwordx4 v[148:149], v[120:123], off offset:16 nt
	s_mov_b64 s[8:9], 0

.LBB0_1101:
	s_mul_i32 s14, s35, 0x4100000
	s_lshl_b64 s[8:9], s[14:15], 1
	s_add_u32 s52, s38, s8
	s_addc_u32 s53, s39, s9
	v_cvt_pk_bf16_f32 v124, v124, v125
	v_cvt_pk_bf16_f32 v125, v126, v127
	v_cvt_pk_bf16_f32 v126, v120, v121
	v_cndmask_b32_e64 v120, 0, 1, s[30:31]
	v_lshl_add_u64 v[150:151], v[150:151], 1, s[52:53]
	v_cvt_pk_bf16_f32 v127, v122, v123
	v_cmp_ne_u32_e64 s[8:9], 1, v120
	s_andn2_b64 vcc, exec, s[30:31]
	s_mov_b64 s[30:31], -1
	global_store_dwordx4 v[150:151], v[124:127], off
	s_cbranch_vccnz .LBB0_1103
	s_mov_b64 s[30:31], 0
	global_store_dwordx4 v[148:149], v[116:119], off offset:512 nt
	global_store_dwordx4 v[148:149], v[112:115], off offset:528 nt

.LBB0_1105:
	v_cvt_pk_bf16_f32 v116, v116, v117
	v_cvt_pk_bf16_f32 v117, v118, v119
	v_cvt_pk_bf16_f32 v118, v112, v113
	v_or_b32_e32 v112, 16, v144
	v_ashrrev_i32_e32 v113, 31, v112
	v_lshlrev_b64 v[112:113], 10, v[112:113]
	v_cvt_pk_bf16_f32 v119, v114, v115
	v_lshl_add_u64 v[114:115], v[112:113], 0, v[146:147]
	v_lshl_add_u64 v[112:113], v[114:115], 2, s[36:37]
	s_and_b64 vcc, exec, s[8:9]
	s_mov_b64 s[30:31], -1
	global_store_dwordx4 v[150:151], v[116:119], off offset:256
	s_cbranch_vccnz .LBB0_1107
	s_mov_b64 s[30:31], 0
	global_store_dwordx4 v[112:113], v[108:111], off nt
	global_store_dwordx4 v[112:113], v[104:107], off offset:16 nt

.LBB0_1109:
	v_lshl_add_u64 v[114:115], v[114:115], 1, s[52:53]
	v_cvt_pk_bf16_f32 v108, v108, v109
	v_cvt_pk_bf16_f32 v109, v110, v111
	v_cvt_pk_bf16_f32 v110, v104, v105
	v_cvt_pk_bf16_f32 v111, v106, v107
	s_and_b64 vcc, exec, s[8:9]
	s_mov_b64 s[30:31], -1
	global_store_dwordx4 v[114:115], v[108:111], off
	s_cbranch_vccnz .LBB0_1111
	s_mov_b64 s[30:31], 0
	global_store_dwordx4 v[112:113], v[100:103], off offset:512 nt
	global_store_dwordx4 v[112:113], v[96:99], off offset:528 nt

.LBB0_1113:
	v_cvt_pk_bf16_f32 v100, v100, v101
	v_cvt_pk_bf16_f32 v101, v102, v103
	v_cvt_pk_bf16_f32 v102, v96, v97
	v_or_b32_e32 v96, 32, v144
	v_ashrrev_i32_e32 v97, 31, v96
	v_lshlrev_b64 v[96:97], 10, v[96:97]
	v_cvt_pk_bf16_f32 v103, v98, v99
	v_lshl_add_u64 v[98:99], v[96:97], 0, v[146:147]
	v_lshl_add_u64 v[96:97], v[98:99], 2, s[36:37]
	s_and_b64 vcc, exec, s[8:9]
	s_mov_b64 s[30:31], -1
	global_store_dwordx4 v[114:115], v[100:103], off offset:256
	s_cbranch_vccnz .LBB0_1115
	s_mov_b64 s[30:31], 0
	global_store_dwordx4 v[96:97], v[92:95], off nt
	global_store_dwordx4 v[96:97], v[88:91], off offset:16 nt

.LBB0_1117:
	v_lshl_add_u64 v[98:99], v[98:99], 1, s[52:53]
	v_cvt_pk_bf16_f32 v92, v92, v93
	v_cvt_pk_bf16_f32 v93, v94, v95
	v_cvt_pk_bf16_f32 v94, v88, v89
	v_cvt_pk_bf16_f32 v95, v90, v91
	s_and_b64 vcc, exec, s[8:9]
	s_mov_b64 s[30:31], -1
	global_store_dwordx4 v[98:99], v[92:95], off
	s_cbranch_vccnz .LBB0_1119
	s_mov_b64 s[30:31], 0
	global_store_dwordx4 v[96:97], v[84:87], off offset:512 nt
	global_store_dwordx4 v[96:97], v[80:83], off offset:528 nt

.LBB0_1121:
	v_cvt_pk_bf16_f32 v84, v84, v85
	v_cvt_pk_bf16_f32 v85, v86, v87
	v_cvt_pk_bf16_f32 v86, v80, v81
	v_or_b32_e32 v80, 48, v144
	v_ashrrev_i32_e32 v81, 31, v80
	v_lshlrev_b64 v[80:81], 10, v[80:81]
	v_cvt_pk_bf16_f32 v87, v82, v83
	v_lshl_add_u64 v[82:83], v[80:81], 0, v[146:147]
	v_lshl_add_u64 v[80:81], v[82:83], 2, s[36:37]
	s_and_b64 vcc, exec, s[8:9]
	s_mov_b64 s[30:31], -1
	global_store_dwordx4 v[98:99], v[84:87], off offset:256
	s_cbranch_vccnz .LBB0_1123
	s_mov_b64 s[30:31], 0
	global_store_dwordx4 v[80:81], v[76:79], off nt
	global_store_dwordx4 v[80:81], v[72:75], off offset:16 nt

.LBB0_1125:
	v_lshl_add_u64 v[82:83], v[82:83], 1, s[52:53]
	v_cvt_pk_bf16_f32 v76, v76, v77
	v_cvt_pk_bf16_f32 v77, v78, v79
	v_cvt_pk_bf16_f32 v78, v72, v73
	v_cvt_pk_bf16_f32 v79, v74, v75
	s_and_b64 vcc, exec, s[8:9]
	s_mov_b64 s[30:31], -1
	global_store_dwordx4 v[82:83], v[76:79], off
	s_cbranch_vccnz .LBB0_1127
	s_mov_b64 s[30:31], 0
	global_store_dwordx4 v[80:81], v[68:71], off offset:512 nt
	global_store_dwordx4 v[80:81], v[64:67], off offset:528 nt

.LBB0_1129:
	v_cvt_pk_bf16_f32 v68, v68, v69
	v_cvt_pk_bf16_f32 v69, v70, v71
	v_cvt_pk_bf16_f32 v70, v64, v65
	v_lshlrev_b64 v[64:65], 10, v[144:145]
	v_lshl_add_u64 v[64:65], v[64:65], 0, v[146:147]
	s_mov_b64 s[30:31], 0x20000
	v_cvt_pk_bf16_f32 v71, v66, v67
	v_lshl_add_u64 v[66:67], v[64:65], 0, s[30:31]
	v_lshl_add_u64 v[64:65], v[66:67], 2, s[36:37]
	s_and_b64 vcc, exec, s[8:9]
	s_mov_b64 s[30:31], -1
	global_store_dwordx4 v[82:83], v[68:71], off offset:256
	s_cbranch_vccnz .LBB0_1131
	s_mov_b64 s[30:31], 0
	global_store_dwordx4 v[64:65], v[60:63], off nt
	global_store_dwordx4 v[64:65], v[56:59], off offset:16 nt

.LBB0_1133:
	v_lshl_add_u64 v[66:67], v[66:67], 1, s[52:53]
	v_cvt_pk_bf16_f32 v60, v60, v61
	v_cvt_pk_bf16_f32 v61, v62, v63
	v_cvt_pk_bf16_f32 v62, v56, v57
	v_cvt_pk_bf16_f32 v63, v58, v59
	s_and_b64 vcc, exec, s[8:9]
	s_mov_b64 s[30:31], -1
	global_store_dwordx4 v[66:67], v[60:63], off
	s_cbranch_vccnz .LBB0_1135
	s_mov_b64 s[30:31], 0
	global_store_dwordx4 v[64:65], v[52:55], off offset:512 nt
	global_store_dwordx4 v[64:65], v[48:51], off offset:528 nt

.LBB0_1137:
	v_cvt_pk_bf16_f32 v52, v52, v53
	v_cvt_pk_bf16_f32 v53, v54, v55
	v_cvt_pk_bf16_f32 v54, v48, v49
	v_lshlrev_b64 v[48:49], 10, v[144:145]
	v_lshl_add_u64 v[48:49], v[48:49], 0, v[146:147]
	v_cvt_pk_bf16_f32 v55, v50, v51
	v_lshl_add_u64 v[50:51], v[48:49], 0, s[24:25]
	v_lshl_add_u64 v[48:49], v[50:51], 2, s[36:37]
	s_and_b64 vcc, exec, s[8:9]
	s_mov_b64 s[30:31], -1
	global_store_dwordx4 v[66:67], v[52:55], off offset:256
	s_cbranch_vccnz .LBB0_1139
	s_mov_b64 s[30:31], 0
	global_store_dwordx4 v[48:49], v[44:47], off nt
	global_store_dwordx4 v[48:49], v[40:43], off offset:16 nt

.LBB0_1141:
	v_lshl_add_u64 v[50:51], v[50:51], 1, s[52:53]
	v_cvt_pk_bf16_f32 v44, v44, v45
	v_cvt_pk_bf16_f32 v45, v46, v47
	v_cvt_pk_bf16_f32 v46, v40, v41
	v_cvt_pk_bf16_f32 v47, v42, v43
	s_and_b64 vcc, exec, s[8:9]
	s_mov_b64 s[30:31], -1
	global_store_dwordx4 v[50:51], v[44:47], off
	s_cbranch_vccnz .LBB0_1143
	s_mov_b64 s[30:31], 0
	global_store_dwordx4 v[48:49], v[36:39], off offset:512 nt
	global_store_dwordx4 v[48:49], v[32:35], off offset:528 nt

.LBB0_1145:
	v_cvt_pk_bf16_f32 v36, v36, v37
	v_cvt_pk_bf16_f32 v37, v38, v39
	v_cvt_pk_bf16_f32 v38, v32, v33
	v_lshlrev_b64 v[32:33], 10, v[144:145]
	v_lshl_add_u64 v[32:33], v[32:33], 0, v[146:147]
	v_cvt_pk_bf16_f32 v39, v34, v35
	v_lshl_add_u64 v[34:35], v[32:33], 0, s[26:27]
	v_lshl_add_u64 v[32:33], v[34:35], 2, s[36:37]
	s_and_b64 vcc, exec, s[8:9]
	s_mov_b64 s[30:31], -1
	global_store_dwordx4 v[50:51], v[36:39], off offset:256
	s_cbranch_vccnz .LBB0_1147
	s_mov_b64 s[30:31], 0
	global_store_dwordx4 v[32:33], v[28:31], off nt
	global_store_dwordx4 v[32:33], v[24:27], off offset:16 nt

.LBB0_1149:
	v_lshl_add_u64 v[34:35], v[34:35], 1, s[52:53]
	v_cvt_pk_bf16_f32 v28, v28, v29
	v_cvt_pk_bf16_f32 v29, v30, v31
	v_cvt_pk_bf16_f32 v30, v24, v25
	v_cvt_pk_bf16_f32 v31, v26, v27
	s_and_b64 vcc, exec, s[8:9]
	s_mov_b64 s[30:31], -1
	global_store_dwordx4 v[34:35], v[28:31], off
	s_cbranch_vccnz .LBB0_1151
	s_mov_b64 s[30:31], 0
	global_store_dwordx4 v[32:33], v[20:23], off offset:512 nt
	global_store_dwordx4 v[32:33], v[16:19], off offset:528 nt

.LBB0_1153:
	v_cvt_pk_bf16_f32 v20, v20, v21
	v_cvt_pk_bf16_f32 v21, v22, v23
	v_cvt_pk_bf16_f32 v22, v16, v17
	v_lshlrev_b64 v[16:17], 10, v[144:145]
	v_lshl_add_u64 v[16:17], v[16:17], 0, v[146:147]
	v_cvt_pk_bf16_f32 v23, v18, v19
	v_lshl_add_u64 v[18:19], v[16:17], 0, s[28:29]
	v_lshl_add_u64 v[16:17], v[18:19], 2, s[36:37]
	s_and_b64 vcc, exec, s[8:9]
	s_mov_b64 s[30:31], -1
	global_store_dwordx4 v[34:35], v[20:23], off offset:256
	s_cbranch_vccnz .LBB0_1155
	s_mov_b64 s[30:31], 0
	global_store_dwordx4 v[16:17], v[12:15], off nt
	global_store_dwordx4 v[16:17], v[8:11], off offset:16 nt

.LBB0_1157:
	v_lshl_add_u64 v[18:19], v[18:19], 1, s[52:53]
	v_cvt_pk_bf16_f32 v12, v12, v13
	v_cvt_pk_bf16_f32 v13, v14, v15
	v_cvt_pk_bf16_f32 v14, v8, v9
	v_cvt_pk_bf16_f32 v15, v10, v11
	s_and_b64 vcc, exec, s[8:9]
	s_mov_b64 s[8:9], -1
	global_store_dwordx4 v[18:19], v[12:15], off
	s_cbranch_vccnz .LBB0_1159
	s_mov_b64 s[8:9], 0
	global_store_dwordx4 v[16:17], v[4:7], off offset:512 nt
	global_store_dwordx4 v[16:17], v[0:3], off offset:528 nt
